# norm phases: write-through stores and no L2 write-back in the grid barriers that follow them
# baseline (speedup 1.0000x reference)
.Lnrm_p1_cpD:
	s_mul_hi_i32 s4, s2, 0x38e38e39
	s_lshr_b32 s5, s4, 31
	s_ashr_i32 s4, s4, 9
	s_add_i32 s4, s4, s5
	s_mul_i32 s5, s4, 0xfffff700
	s_add_i32 s5, s2, s5
	s_cmpk_lt_i32 s5, 0x100
	s_cselect_b32 s8, 1, 0
	s_and_b32 s100, s100, 0x100
	s_or_b32 s100, s100, s8
	v_readlane_b32 s9, v255, 18
	s_and_b32 s8, s8, s9
	s_cmp_lg_u32 s8, 0
	s_cbranch_scc0 .Lnrm_p1_nopart
	v_readlane_b32 s12, v255, 14
	v_readlane_b32 s13, v255, 15
	s_lshl_b32 s8, s4, 8
	s_add_i32 s8, s8, s5
	s_lshl_b32 s8, s8, 13
	s_add_u32 s12, s12, s8
	s_addc_u32 s13, s13, 0
	s_add_u32 s12, s12, 0x1000
	s_addc_u32 s13, s13, 0
	v_readlane_b32 s10, v255, 16
	v_readlane_b32 s11, v255, 17
	s_nop 0
	s_add_u32 s10, s10, 0x1000
	s_addc_u32 s11, s11, 0
	s_lshl_b32 s8, s2, 13
	s_add_u32 s8, s8, 0xb601000
	s_add_u32 s8, s54, s8
	s_addc_u32 s9, s55, 0
	s_mov_b64 s[14:15], s[12:13]
	global_load_dwordx4 v[96:99], v176, s[14:15] offset:-4096
	global_load_dwordx4 v[128:131], v176, s[14:15] offset:-3072
	s_add_u32 s14, s14, 0x800000
	s_addc_u32 s15, s15, 0
	global_load_dwordx4 v[100:103], v176, s[14:15] offset:-4096
	global_load_dwordx4 v[132:135], v176, s[14:15] offset:-3072
	s_add_u32 s14, s14, 0x800000
	s_addc_u32 s15, s15, 0
	global_load_dwordx4 v[104:107], v176, s[14:15] offset:-4096
	global_load_dwordx4 v[136:139], v176, s[14:15] offset:-3072
	s_add_u32 s14, s14, 0x800000
	s_addc_u32 s15, s15, 0
	global_load_dwordx4 v[108:111], v176, s[14:15] offset:-4096
	global_load_dwordx4 v[140:143], v176, s[14:15] offset:-3072
	s_add_u32 s14, s14, 0x800000
	s_addc_u32 s15, s15, 0
	global_load_dwordx4 v[112:115], v176, s[14:15] offset:-4096
	global_load_dwordx4 v[144:147], v176, s[14:15] offset:-3072
	s_add_u32 s14, s14, 0x800000
	s_addc_u32 s15, s15, 0
	global_load_dwordx4 v[116:119], v176, s[14:15] offset:-4096
	global_load_dwordx4 v[148:151], v176, s[14:15] offset:-3072
	s_add_u32 s14, s14, 0x800000
	s_addc_u32 s15, s15, 0
	global_load_dwordx4 v[120:123], v176, s[14:15] offset:-4096
	global_load_dwordx4 v[152:155], v176, s[14:15] offset:-3072
	s_add_u32 s14, s14, 0x800000
	s_addc_u32 s15, s15, 0
	global_load_dwordx4 v[124:127], v176, s[14:15] offset:-4096
	global_load_dwordx4 v[156:159], v176, s[14:15] offset:-3072
	global_load_dwordx4 v[160:163], v176, s[10:11] offset:-4096
	global_load_dwordx4 v[164:167], v176, s[10:11] offset:-3072
	s_waitcnt vmcnt(0)
	v_pk_add_f32 v[96:97], v[96:97], v[100:101]
	v_pk_add_f32 v[98:99], v[98:99], v[102:103]
	v_pk_add_f32 v[96:97], v[96:97], v[104:105]
	v_pk_add_f32 v[98:99], v[98:99], v[106:107]
	v_pk_add_f32 v[96:97], v[96:97], v[108:109]
	v_pk_add_f32 v[98:99], v[98:99], v[110:111]
	v_pk_add_f32 v[96:97], v[96:97], v[112:113]
	v_pk_add_f32 v[98:99], v[98:99], v[114:115]
	v_pk_add_f32 v[96:97], v[96:97], v[116:117]
	v_pk_add_f32 v[98:99], v[98:99], v[118:119]
	v_pk_add_f32 v[96:97], v[96:97], v[120:121]
	v_pk_add_f32 v[98:99], v[98:99], v[122:123]
	v_pk_add_f32 v[96:97], v[96:97], v[124:125]
	v_pk_add_f32 v[98:99], v[98:99], v[126:127]
	v_pk_add_f32 v[128:129], v[128:129], v[132:133]
	v_pk_add_f32 v[130:131], v[130:131], v[134:135]
	v_pk_add_f32 v[128:129], v[128:129], v[136:137]
	v_pk_add_f32 v[130:131], v[130:131], v[138:139]
	v_pk_add_f32 v[128:129], v[128:129], v[140:141]
	v_pk_add_f32 v[130:131], v[130:131], v[142:143]
	v_pk_add_f32 v[128:129], v[128:129], v[144:145]
	v_pk_add_f32 v[130:131], v[130:131], v[146:147]
	v_pk_add_f32 v[128:129], v[128:129], v[148:149]
	v_pk_add_f32 v[130:131], v[130:131], v[150:151]
	v_pk_add_f32 v[128:129], v[128:129], v[152:153]
	v_pk_add_f32 v[130:131], v[130:131], v[154:155]
	v_pk_add_f32 v[128:129], v[128:129], v[156:157]
	v_pk_add_f32 v[130:131], v[130:131], v[158:159]
	v_pk_fma_f32 v[0:1], v[96:97], v[160:161], v[0:1]
	v_pk_fma_f32 v[2:3], v[98:99], v[162:163], v[2:3]
	v_pk_fma_f32 v[4:5], v[128:129], v[164:165], v[4:5]
	v_pk_fma_f32 v[6:7], v[130:131], v[166:167], v[6:7]
	global_store_dwordx4 v176, v[0:3], s[8:9] offset:-4096 sc1
	global_store_dwordx4 v176, v[4:7], s[8:9] offset:-3072 sc1
	s_mov_b64 s[14:15], s[12:13]
	global_load_dwordx4 v[96:99], v176, s[14:15] offset:-2048
	global_load_dwordx4 v[128:131], v176, s[14:15] offset:-1024
	s_add_u32 s14, s14, 0x800000
	s_addc_u32 s15, s15, 0
	global_load_dwordx4 v[100:103], v176, s[14:15] offset:-2048
	global_load_dwordx4 v[132:135], v176, s[14:15] offset:-1024
	s_add_u32 s14, s14, 0x800000
	s_addc_u32 s15, s15, 0
	global_load_dwordx4 v[104:107], v176, s[14:15] offset:-2048
	global_load_dwordx4 v[136:139], v176, s[14:15] offset:-1024
	s_add_u32 s14, s14, 0x800000
	s_addc_u32 s15, s15, 0
	global_load_dwordx4 v[108:111], v176, s[14:15] offset:-2048
	global_load_dwordx4 v[140:143], v176, s[14:15] offset:-1024
	s_add_u32 s14, s14, 0x800000
	s_addc_u32 s15, s15, 0
	global_load_dwordx4 v[112:115], v176, s[14:15] offset:-2048
	global_load_dwordx4 v[144:147], v176, s[14:15] offset:-1024
	s_add_u32 s14, s14, 0x800000
	s_addc_u32 s15, s15, 0
	global_load_dwordx4 v[116:119], v176, s[14:15] offset:-2048
	global_load_dwordx4 v[148:151], v176, s[14:15] offset:-1024
	s_add_u32 s14, s14, 0x800000
	s_addc_u32 s15, s15, 0
	global_load_dwordx4 v[120:123], v176, s[14:15] offset:-2048
	global_load_dwordx4 v[152:155], v176, s[14:15] offset:-1024
	s_add_u32 s14, s14, 0x800000
	s_addc_u32 s15, s15, 0
	global_load_dwordx4 v[124:127], v176, s[14:15] offset:-2048
	global_load_dwordx4 v[156:159], v176, s[14:15] offset:-1024
	global_load_dwordx4 v[160:163], v176, s[10:11] offset:-2048
	global_load_dwordx4 v[164:167], v176, s[10:11] offset:-1024
	s_waitcnt vmcnt(0)
	v_pk_add_f32 v[96:97], v[96:97], v[100:101]
	v_pk_add_f32 v[98:99], v[98:99], v[102:103]
	v_pk_add_f32 v[96:97], v[96:97], v[104:105]
	v_pk_add_f32 v[98:99], v[98:99], v[106:107]
	v_pk_add_f32 v[96:97], v[96:97], v[108:109]
	v_pk_add_f32 v[98:99], v[98:99], v[110:111]
	v_pk_add_f32 v[96:97], v[96:97], v[112:113]
	v_pk_add_f32 v[98:99], v[98:99], v[114:115]
	v_pk_add_f32 v[96:97], v[96:97], v[116:117]
	v_pk_add_f32 v[98:99], v[98:99], v[118:119]
	v_pk_add_f32 v[96:97], v[96:97], v[120:121]
	v_pk_add_f32 v[98:99], v[98:99], v[122:123]
	v_pk_add_f32 v[96:97], v[96:97], v[124:125]
	v_pk_add_f32 v[98:99], v[98:99], v[126:127]
	v_pk_add_f32 v[128:129], v[128:129], v[132:133]
	v_pk_add_f32 v[130:131], v[130:131], v[134:135]
	v_pk_add_f32 v[128:129], v[128:129], v[136:137]
	v_pk_add_f32 v[130:131], v[130:131], v[138:139]
	v_pk_add_f32 v[128:129], v[128:129], v[140:141]
	v_pk_add_f32 v[130:131], v[130:131], v[142:143]
	v_pk_add_f32 v[128:129], v[128:129], v[144:145]
	v_pk_add_f32 v[130:131], v[130:131], v[146:147]
	v_pk_add_f32 v[128:129], v[128:129], v[148:149]
	v_pk_add_f32 v[130:131], v[130:131], v[150:151]
	v_pk_add_f32 v[128:129], v[128:129], v[152:153]
	v_pk_add_f32 v[130:131], v[130:131], v[154:155]
	v_pk_add_f32 v[128:129], v[128:129], v[156:157]
	v_pk_add_f32 v[130:131], v[130:131], v[158:159]
	v_pk_fma_f32 v[8:9], v[96:97], v[160:161], v[8:9]
	v_pk_fma_f32 v[10:11], v[98:99], v[162:163], v[10:11]
	v_pk_fma_f32 v[12:13], v[128:129], v[164:165], v[12:13]
	v_pk_fma_f32 v[14:15], v[130:131], v[166:167], v[14:15]
	global_store_dwordx4 v176, v[8:11], s[8:9] offset:-2048 sc1
	global_store_dwordx4 v176, v[12:15], s[8:9] offset:-1024 sc1
	s_mov_b64 s[14:15], s[12:13]
	global_load_dwordx4 v[96:99], v176, s[14:15] offset:0
	global_load_dwordx4 v[128:131], v176, s[14:15] offset:1024
	s_add_u32 s14, s14, 0x800000
	s_addc_u32 s15, s15, 0
	global_load_dwordx4 v[100:103], v176, s[14:15] offset:0
	global_load_dwordx4 v[132:135], v176, s[14:15] offset:1024
	s_add_u32 s14, s14, 0x800000
	s_addc_u32 s15, s15, 0
	global_load_dwordx4 v[104:107], v176, s[14:15] offset:0
	global_load_dwordx4 v[136:139], v176, s[14:15] offset:1024
	s_add_u32 s14, s14, 0x800000
	s_addc_u32 s15, s15, 0
	global_load_dwordx4 v[108:111], v176, s[14:15] offset:0
	global_load_dwordx4 v[140:143], v176, s[14:15] offset:1024
	s_add_u32 s14, s14, 0x800000
	s_addc_u32 s15, s15, 0
	global_load_dwordx4 v[112:115], v176, s[14:15] offset:0
	global_load_dwordx4 v[144:147], v176, s[14:15] offset:1024
	s_add_u32 s14, s14, 0x800000
	s_addc_u32 s15, s15, 0
	global_load_dwordx4 v[116:119], v176, s[14:15] offset:0
	global_load_dwordx4 v[148:151], v176, s[14:15] offset:1024
	s_add_u32 s14, s14, 0x800000
	s_addc_u32 s15, s15, 0
	global_load_dwordx4 v[120:123], v176, s[14:15] offset:0
	global_load_dwordx4 v[152:155], v176, s[14:15] offset:1024
	s_add_u32 s14, s14, 0x800000
	s_addc_u32 s15, s15, 0
	global_load_dwordx4 v[124:127], v176, s[14:15] offset:0
	global_load_dwordx4 v[156:159], v176, s[14:15] offset:1024
	global_load_dwordx4 v[160:163], v176, s[10:11] offset:0
	global_load_dwordx4 v[164:167], v176, s[10:11] offset:1024
	s_waitcnt vmcnt(0)
	v_pk_add_f32 v[96:97], v[96:97], v[100:101]
	v_pk_add_f32 v[98:99], v[98:99], v[102:103]
	v_pk_add_f32 v[96:97], v[96:97], v[104:105]
	v_pk_add_f32 v[98:99], v[98:99], v[106:107]
	v_pk_add_f32 v[96:97], v[96:97], v[108:109]
	v_pk_add_f32 v[98:99], v[98:99], v[110:111]
	v_pk_add_f32 v[96:97], v[96:97], v[112:113]
	v_pk_add_f32 v[98:99], v[98:99], v[114:115]
	v_pk_add_f32 v[96:97], v[96:97], v[116:117]
	v_pk_add_f32 v[98:99], v[98:99], v[118:119]
	v_pk_add_f32 v[96:97], v[96:97], v[120:121]
	v_pk_add_f32 v[98:99], v[98:99], v[122:123]
	v_pk_add_f32 v[96:97], v[96:97], v[124:125]
	v_pk_add_f32 v[98:99], v[98:99], v[126:127]
	v_pk_add_f32 v[128:129], v[128:129], v[132:133]
	v_pk_add_f32 v[130:131], v[130:131], v[134:135]
	v_pk_add_f32 v[128:129], v[128:129], v[136:137]
	v_pk_add_f32 v[130:131], v[130:131], v[138:139]
	v_pk_add_f32 v[128:129], v[128:129], v[140:141]
	v_pk_add_f32 v[130:131], v[130:131], v[142:143]
	v_pk_add_f32 v[128:129], v[128:129], v[144:145]
	v_pk_add_f32 v[130:131], v[130:131], v[146:147]
	v_pk_add_f32 v[128:129], v[128:129], v[148:149]
	v_pk_add_f32 v[130:131], v[130:131], v[150:151]
	v_pk_add_f32 v[128:129], v[128:129], v[152:153]
	v_pk_add_f32 v[130:131], v[130:131], v[154:155]
	v_pk_add_f32 v[128:129], v[128:129], v[156:157]
	v_pk_add_f32 v[130:131], v[130:131], v[158:159]
	v_pk_fma_f32 v[16:17], v[96:97], v[160:161], v[16:17]
	v_pk_fma_f32 v[18:19], v[98:99], v[162:163], v[18:19]
	v_pk_fma_f32 v[20:21], v[128:129], v[164:165], v[20:21]
	v_pk_fma_f32 v[22:23], v[130:131], v[166:167], v[22:23]
	global_store_dwordx4 v176, v[16:19], s[8:9] offset:0 sc1
	global_store_dwordx4 v176, v[20:23], s[8:9] offset:1024 sc1
	s_mov_b64 s[14:15], s[12:13]
	global_load_dwordx4 v[96:99], v176, s[14:15] offset:2048
	global_load_dwordx4 v[128:131], v176, s[14:15] offset:3072
	s_add_u32 s14, s14, 0x800000
	s_addc_u32 s15, s15, 0
	global_load_dwordx4 v[100:103], v176, s[14:15] offset:2048
	global_load_dwordx4 v[132:135], v176, s[14:15] offset:3072
	s_add_u32 s14, s14, 0x800000
	s_addc_u32 s15, s15, 0
	global_load_dwordx4 v[104:107], v176, s[14:15] offset:2048
	global_load_dwordx4 v[136:139], v176, s[14:15] offset:3072
	s_add_u32 s14, s14, 0x800000
	s_addc_u32 s15, s15, 0
	global_load_dwordx4 v[108:111], v176, s[14:15] offset:2048
	global_load_dwordx4 v[140:143], v176, s[14:15] offset:3072
	s_add_u32 s14, s14, 0x800000
	s_addc_u32 s15, s15, 0
	global_load_dwordx4 v[112:115], v176, s[14:15] offset:2048
	global_load_dwordx4 v[144:147], v176, s[14:15] offset:3072
	s_add_u32 s14, s14, 0x800000
	s_addc_u32 s15, s15, 0
	global_load_dwordx4 v[116:119], v176, s[14:15] offset:2048
	global_load_dwordx4 v[148:151], v176, s[14:15] offset:3072
	s_add_u32 s14, s14, 0x800000
	s_addc_u32 s15, s15, 0
	global_load_dwordx4 v[120:123], v176, s[14:15] offset:2048
	global_load_dwordx4 v[152:155], v176, s[14:15] offset:3072
	s_add_u32 s14, s14, 0x800000
	s_addc_u32 s15, s15, 0
	global_load_dwordx4 v[124:127], v176, s[14:15] offset:2048
	global_load_dwordx4 v[156:159], v176, s[14:15] offset:3072
	global_load_dwordx4 v[160:163], v176, s[10:11] offset:2048
	global_load_dwordx4 v[164:167], v176, s[10:11] offset:3072
	s_waitcnt vmcnt(0)
	v_pk_add_f32 v[96:97], v[96:97], v[100:101]
	v_pk_add_f32 v[98:99], v[98:99], v[102:103]
	v_pk_add_f32 v[96:97], v[96:97], v[104:105]
	v_pk_add_f32 v[98:99], v[98:99], v[106:107]
	v_pk_add_f32 v[96:97], v[96:97], v[108:109]
	v_pk_add_f32 v[98:99], v[98:99], v[110:111]
	v_pk_add_f32 v[96:97], v[96:97], v[112:113]
	v_pk_add_f32 v[98:99], v[98:99], v[114:115]
	v_pk_add_f32 v[96:97], v[96:97], v[116:117]
	v_pk_add_f32 v[98:99], v[98:99], v[118:119]
	v_pk_add_f32 v[96:97], v[96:97], v[120:121]
	v_pk_add_f32 v[98:99], v[98:99], v[122:123]
	v_pk_add_f32 v[96:97], v[96:97], v[124:125]
	v_pk_add_f32 v[98:99], v[98:99], v[126:127]
	v_pk_add_f32 v[128:129], v[128:129], v[132:133]
	v_pk_add_f32 v[130:131], v[130:131], v[134:135]
	v_pk_add_f32 v[128:129], v[128:129], v[136:137]
	v_pk_add_f32 v[130:131], v[130:131], v[138:139]
	v_pk_add_f32 v[128:129], v[128:129], v[140:141]
	v_pk_add_f32 v[130:131], v[130:131], v[142:143]
	v_pk_add_f32 v[128:129], v[128:129], v[144:145]
	v_pk_add_f32 v[130:131], v[130:131], v[146:147]
	v_pk_add_f32 v[128:129], v[128:129], v[148:149]
	v_pk_add_f32 v[130:131], v[130:131], v[150:151]
	v_pk_add_f32 v[128:129], v[128:129], v[152:153]
	v_pk_add_f32 v[130:131], v[130:131], v[154:155]
	v_pk_add_f32 v[128:129], v[128:129], v[156:157]
	v_pk_add_f32 v[130:131], v[130:131], v[158:159]
	v_pk_fma_f32 v[24:25], v[96:97], v[160:161], v[24:25]
	v_pk_fma_f32 v[26:27], v[98:99], v[162:163], v[26:27]
	v_pk_fma_f32 v[28:29], v[128:129], v[164:165], v[28:29]
	v_pk_fma_f32 v[30:31], v[130:131], v[166:167], v[30:31]
	global_store_dwordx4 v176, v[24:27], s[8:9] offset:2048 sc1
	global_store_dwordx4 v176, v[28:31], s[8:9] offset:3072 sc1

.Lnrm_p1_wd:
	v_pk_mul_f32 v[0:1], v[178:179], v[0:1]
	v_pk_add_f32 v[172:173], v[128:129], 1.0 op_sel_hi:[1,0]
	v_pk_fma_f32 v[0:1], v[172:173], v[0:1], v[96:97]
	v_pk_mul_f32 v[2:3], v[180:181], v[2:3]
	v_pk_add_f32 v[174:175], v[130:131], 1.0 op_sel_hi:[1,0]
	v_pk_fma_f32 v[2:3], v[174:175], v[2:3], v[98:99]
	v_cvt_pk_bf16_f32 v168, v0, v1
	v_cvt_pk_bf16_f32 v169, v2, v3
	global_store_dwordx2 v210, v[168:169], s[8:9] offset:0 sc1
	s_nop 0
	v_pk_mul_f32 v[4:5], v[182:183], v[4:5]
	v_pk_add_f32 v[172:173], v[132:133], 1.0 op_sel_hi:[1,0]
	v_pk_fma_f32 v[4:5], v[172:173], v[4:5], v[100:101]
	v_pk_mul_f32 v[6:7], v[184:185], v[6:7]
	v_pk_add_f32 v[174:175], v[134:135], 1.0 op_sel_hi:[1,0]
	v_pk_fma_f32 v[6:7], v[174:175], v[6:7], v[102:103]
	v_cvt_pk_bf16_f32 v168, v4, v5
	v_cvt_pk_bf16_f32 v169, v6, v7
	global_store_dwordx2 v210, v[168:169], s[8:9] offset:512 sc1
	s_nop 0
	v_pk_mul_f32 v[8:9], v[186:187], v[8:9]
	v_pk_add_f32 v[172:173], v[136:137], 1.0 op_sel_hi:[1,0]
	v_pk_fma_f32 v[8:9], v[172:173], v[8:9], v[104:105]
	v_pk_mul_f32 v[10:11], v[188:189], v[10:11]
	v_pk_add_f32 v[174:175], v[138:139], 1.0 op_sel_hi:[1,0]
	v_pk_fma_f32 v[10:11], v[174:175], v[10:11], v[106:107]
	v_cvt_pk_bf16_f32 v168, v8, v9
	v_cvt_pk_bf16_f32 v169, v10, v11
	global_store_dwordx2 v210, v[168:169], s[8:9] offset:1024 sc1
	s_nop 0
	v_pk_mul_f32 v[12:13], v[190:191], v[12:13]
	v_pk_add_f32 v[172:173], v[140:141], 1.0 op_sel_hi:[1,0]
	v_pk_fma_f32 v[12:13], v[172:173], v[12:13], v[108:109]
	v_pk_mul_f32 v[14:15], v[192:193], v[14:15]
	v_pk_add_f32 v[174:175], v[142:143], 1.0 op_sel_hi:[1,0]
	v_pk_fma_f32 v[14:15], v[174:175], v[14:15], v[110:111]
	v_cvt_pk_bf16_f32 v168, v12, v13
	v_cvt_pk_bf16_f32 v169, v14, v15
	global_store_dwordx2 v210, v[168:169], s[8:9] offset:1536 sc1
	s_nop 0
	v_pk_mul_f32 v[16:17], v[194:195], v[16:17]
	v_pk_add_f32 v[172:173], v[144:145], 1.0 op_sel_hi:[1,0]
	v_pk_fma_f32 v[16:17], v[172:173], v[16:17], v[112:113]
	v_pk_mul_f32 v[18:19], v[196:197], v[18:19]
	v_pk_add_f32 v[174:175], v[146:147], 1.0 op_sel_hi:[1,0]
	v_pk_fma_f32 v[18:19], v[174:175], v[18:19], v[114:115]
	v_cvt_pk_bf16_f32 v168, v16, v17
	v_cvt_pk_bf16_f32 v169, v18, v19
	global_store_dwordx2 v210, v[168:169], s[8:9] offset:2048 sc1
	s_nop 0
	v_pk_mul_f32 v[20:21], v[198:199], v[20:21]
	v_pk_add_f32 v[172:173], v[148:149], 1.0 op_sel_hi:[1,0]
	v_pk_fma_f32 v[20:21], v[172:173], v[20:21], v[116:117]
	v_pk_mul_f32 v[22:23], v[200:201], v[22:23]
	v_pk_add_f32 v[174:175], v[150:151], 1.0 op_sel_hi:[1,0]
	v_pk_fma_f32 v[22:23], v[174:175], v[22:23], v[118:119]
	v_cvt_pk_bf16_f32 v168, v20, v21
	v_cvt_pk_bf16_f32 v169, v22, v23
	global_store_dwordx2 v210, v[168:169], s[8:9] offset:2560 sc1
	s_nop 0
	v_pk_mul_f32 v[24:25], v[202:203], v[24:25]
	v_pk_add_f32 v[172:173], v[152:153], 1.0 op_sel_hi:[1,0]
	v_pk_fma_f32 v[24:25], v[172:173], v[24:25], v[120:121]
	v_pk_mul_f32 v[26:27], v[204:205], v[26:27]
	v_pk_add_f32 v[174:175], v[154:155], 1.0 op_sel_hi:[1,0]
	v_pk_fma_f32 v[26:27], v[174:175], v[26:27], v[122:123]
	v_cvt_pk_bf16_f32 v168, v24, v25
	v_cvt_pk_bf16_f32 v169, v26, v27
	global_store_dwordx2 v210, v[168:169], s[8:9] offset:3072 sc1
	s_nop 0
	v_pk_mul_f32 v[28:29], v[206:207], v[28:29]
	v_pk_add_f32 v[172:173], v[156:157], 1.0 op_sel_hi:[1,0]
	v_pk_fma_f32 v[28:29], v[172:173], v[28:29], v[124:125]
	v_pk_mul_f32 v[30:31], v[208:209], v[30:31]
	v_pk_add_f32 v[174:175], v[158:159], 1.0 op_sel_hi:[1,0]
	v_pk_fma_f32 v[30:31], v[174:175], v[30:31], v[126:127]
	v_cvt_pk_bf16_f32 v168, v28, v29
	v_cvt_pk_bf16_f32 v169, v30, v31
	global_store_dwordx2 v210, v[168:169], s[8:9] offset:3584 sc1
	s_nop 0
	s_mov_b32 s2, s3
	s_mov_b32 s3, s101
	s_xor_b32 s100, s100, 0x100
	s_cmpk_lt_i32 s2, 0x2400
	s_cbranch_scc0 .Lnrm_p1_exit
	s_cmpk_lt_i32 s3, 0x2400
	s_cbranch_scc1 .Lnrm_p1_w16
	s_waitcnt vmcnt(8)
	s_branch .Lnrm_p1_top

.Lnrm_p1_exit:
.LBB0_620:
	s_waitcnt vmcnt(0)
	s_barrier
	s_mov_b64 s[2:3], exec
	v_readlane_b32 s4, v253, 42
	v_readlane_b32 s5, v253, 43
	s_and_b64 s[4:5], s[2:3], s[4:5]
	s_mov_b64 exec, s[4:5]
	s_cbranch_execz .LBB0_664
	v_readlane_b32 s6, v253, 39
	v_readlane_b32 s7, v253, 40
	v_readlane_b32 s8, v253, 41
	v_readlane_b32 s9, v255, 20
	v_mov_b32_e32 v0, 0x23fc0
	ds_read2_b32 v[4:5], v0 offset1:1
	s_add_i32 s9, s9, 1
	v_writelane_b32 v255, s9, 20
	s_lshl_b32 s10, s8, 8
	s_add_i32 s10, s10, 0x1400
	v_mov_b32_e32 v0, s10
	v_mov_b32_e32 v1, 1
	global_atomic_add v2, v0, v1, s[6:7] sc0
	buffer_inv sc1
	s_waitcnt vmcnt(0) lgkmcnt(0)
	v_readfirstlane_b32 s11, v2
	v_readfirstlane_b32 s15, v4
	v_readfirstlane_b32 s14, v5
	s_add_i32 s11, s11, 1
	s_mul_i32 s15, s15, s9
	s_cmp_lg_u32 s11, s15
	s_cbranch_scc1 .Lgb2_wait
	s_mov_b64 exec, 0xffff
	v_mbcnt_lo_u32_b32 v3, -1, 0
	v_lshlrev_b32_e32 v3, 8, v3
	v_add_u32_e32 v3, 0x2480, v3
	v_mov_b32_e32 v1, 1
	global_atomic_add v3, v1, s[6:7]
	s_mov_b64 exec, 1

.Lnrm_p7_exit:
.LBB0_1325:
	s_waitcnt vmcnt(0)
	s_barrier
	s_mov_b64 s[2:3], exec
	v_readlane_b32 s4, v253, 42
	v_readlane_b32 s5, v253, 43
	s_and_b64 s[4:5], s[2:3], s[4:5]
	s_cmp_lg_u64 s[78:79], 0
	s_cselect_b64 s[4:5], 0, s[4:5]
	s_movk_i32 s92, 0x2c00
	s_mov_b64 exec, s[4:5]
	s_cbranch_execz .LBB0_1369
	v_readlane_b32 s6, v253, 39
	v_readlane_b32 s7, v253, 40
	v_readlane_b32 s8, v253, 41
	v_readlane_b32 s9, v255, 20
	v_mov_b32_e32 v0, 0x23fc0
	ds_read2_b32 v[4:5], v0 offset1:1
	s_add_i32 s9, s9, 1
	v_writelane_b32 v255, s9, 20
	s_lshl_b32 s10, s8, 8
	s_add_i32 s10, s10, 0x1400
	v_mov_b32_e32 v0, s10
	v_mov_b32_e32 v1, 1
	global_atomic_add v2, v0, v1, s[6:7] sc0
	buffer_inv sc1
	s_waitcnt vmcnt(0) lgkmcnt(0)
	v_readfirstlane_b32 s11, v2
	v_readfirstlane_b32 s15, v4
	v_readfirstlane_b32 s14, v5
	s_add_i32 s11, s11, 1
	s_mul_i32 s15, s15, s9
	s_cmp_lg_u32 s11, s15
	s_cbranch_scc1 .Lgb8_wait
	s_mov_b64 exec, 0xffff
	v_mbcnt_lo_u32_b32 v3, -1, 0
	v_lshlrev_b32_e32 v3, 8, v3
	v_add_u32_e32 v3, 0x2480, v3
	v_mov_b32_e32 v1, 1
	global_atomic_add v3, v1, s[6:7]
	s_mov_b64 exec, 1
